# GEMM: first k-iteration peeled with inline-zero SrcC for the first MFMA of every accumulator; per-tile accumulator zeroing removed
# speedup vs baseline: 1.0039x; 1.0016x over previous
; #define PG8_STAGE(bufoff, gbase, voff) do { _Pragma("unroll") for (int _i = 0; _i < 2; ++_i) \
;         __builtin_amdgcn_global_load_lds((const unsigned*)((const char*)(gbase) + (voff)[_i]), (LAS unsigned*)(lds + (bufoff) + ldsw + _i * 8192), 16, 0, 0); } while (0)
; #define PG8_LDA(dst, b, h) do { _Pragma("unroll") for (int m = 0; m < 4; ++m) _Pragma("unroll") for (int k = 0; k < 2; ++k) dst[m][k] = *(const LAS bf16x8*)(lds + PG8_SA(b, h) + aoff + m * 2048 + k * 1024); } while (0)
; #define PG8_LDB(dst, b, h) do { _Pragma("unroll") for (int n = 0; n < 2; ++n) _Pragma("unroll") for (int k = 0; k < 2; ++k) dst[n][k] = *(const LAS bf16x8*)(lds + PG8_SB(b, h) + boff + n * 2048 + k * 1024); } while (0)
; #define PG8_MMA(ai, bj, At, Bt) do { __builtin_amdgcn_s_setprio(1); _Pragma("unroll") for (int m = 0; m < 4; ++m) _Pragma("unroll") for (int n = 0; n < 2; ++n) _Pragma("unroll") for (int k = 0; k < 2; ++k) \
;         acc[ai][bj][m][n] = __builtin_amdgcn_mfma_f32_16x16x32_bf16(Bt[n][k], At[m][k], acc[ai][bj][m][n], 0, 0, 0); __builtin_amdgcn_s_setprio(0); } while (0)
; #define PG8_BAR __builtin_amdgcn_s_barrier()
; template <class Epi>
; __device__ __forceinline__ void gemm_phase(LAS unsigned char* lds, const Gemm g, const StaticOrder& S, const Epi& E) {
;     ...
;     for (;;) {
;         const bool has_next = S.next(ui + 1, nxt);
;         const char* nA = has_next ? (const char*)g.A + (size_t)nxt.pm * tstep : cA; const char* nB = has_next ? (const char*)g.Bt + (size_t)nxt.pn * tstep : cB;
;         for (int t = 0; t < nt; t += 2) {
;             const bool last = (t == nt - 2);
;             const char* a1 = cA + (size_t)(t + 1) * kstep;
;             const char* a2 = last ? nA : cA + (size_t)(t + 2) * kstep; const char* b2 = last ? nB : cB + (size_t)(t + 2) * kstep;
;             const char* a3 = a2 + kstep; const char* b3 = b2 + kstep;
;             PG8_LDB(B0, 0, 0); PG8_LDB(B1, 0, 1); PG8_SCHED; PG8_LDA(At, 0, 0); PG8_STAGE(PG8_SA(1, 1), a1 + hstep, voffA);
;             PG8_WAIT_V(8); PG8_WAIT_L(0); PG8_BAR; PG8_MMA(0, 0, At, B0); PG8_MMA(0, 1, At, B1); PG8_BAR; PG8_SCHED;
;             PG8_LDA(At, 0, 1); PG8_STAGE(PG8_SB(0, 0), b2, voffB); PG8_STAGE(PG8_SB(0, 1), b2 + hstep, voffB); PG8_STAGE(PG8_SA(0, 0), a2, voffA);
;             PG8_WAIT_V(8); PG8_WAIT_L(0); PG8_BAR; PG8_MMA(1, 0, At, B0); PG8_MMA(1, 1, At, B1); PG8_BAR; PG8_SCHED;
.LBB0_221:
	s_add_u32 s0, s6, 0x80
	s_addc_u32 s1, s7, 0
	s_add_u32 s6, s4, 0x100
	s_addc_u32 s7, s5, 0
	s_mov_b32 s4, 0
	s_waitcnt vmcnt(0)
	s_add_i32 s71, s4, 2
	s_add_u32 s72, s0, 0x80
	s_addc_u32 s5, s1, 0
	s_add_i32 s74, 0, 0x10000
	s_cmp_eq_u32 s62, s4
	s_cselect_b32 s5, s49, s5
	s_cselect_b32 s4, s48, s72
	s_cselect_b32 s73, s51, s7
	s_cselect_b32 s72, s50, s6
	s_add_i32 s75, 0, 0x14000
	v_add_u32_e32 v140, s74, v245
	v_add_u32_e32 v156, s75, v245
	ds_read_b128 v[128:131], v140
	ds_read_b128 v[132:135], v140 offset:1024
	ds_read_b128 v[136:139], v140 offset:2048
	ds_read_b128 v[140:143], v140 offset:3072
	ds_read_b128 v[144:147], v156
	ds_read_b128 v[148:151], v156 offset:1024
	ds_read_b128 v[152:155], v156 offset:2048
	ds_read_b128 v[156:159], v156 offset:3072
	v_lshl_add_u64 v[212:213], s[0:1], 0, v[208:209]
	s_add_i32 m0, s55, 0xc000
	ds_read_b128 v[160:163], v247
	ds_read_b128 v[164:167], v247 offset:1024
	ds_read_b128 v[168:171], v247 offset:2048
	ds_read_b128 v[172:175], v247 offset:3072
	ds_read_b128 v[176:179], v247 offset:4096
	ds_read_b128 v[180:183], v247 offset:5120
	ds_read_b128 v[184:187], v247 offset:6144
	ds_read_b128 v[188:191], v247 offset:7168
	global_load_lds_dwordx4 v[212:213], off
	v_lshl_add_u64 v[212:213], s[0:1], 0, v[210:211]
	s_add_i32 m0, s55, 0xe000
	s_nop 0
	global_load_lds_dwordx4 v[212:213], off
	s_waitcnt vmcnt(8)
	s_waitcnt lgkmcnt(0)
	s_barrier
	s_setprio 1
	s_waitcnt lgkmcnt(0)
	v_mfma_f32_16x16x32_bf16 v[124:127], v[128:131], v[160:163], 0
	v_mfma_f32_16x16x32_bf16 v[120:123], v[136:139], v[160:163], 0
	v_mfma_f32_16x16x32_bf16 v[108:111], v[128:131], v[168:171], 0
	v_mfma_f32_16x16x32_bf16 v[104:107], v[136:139], v[168:171], 0
	v_mfma_f32_16x16x32_bf16 v[92:95], v[128:131], v[176:179], 0
	v_mfma_f32_16x16x32_bf16 v[88:91], v[136:139], v[176:179], 0
	v_mfma_f32_16x16x32_bf16 v[76:79], v[128:131], v[184:187], 0
	v_mfma_f32_16x16x32_bf16 v[72:75], v[136:139], v[184:187], 0
	v_mfma_f32_16x16x32_bf16 v[124:127], v[132:135], v[164:167], v[124:127]
	v_mfma_f32_16x16x32_bf16 v[120:123], v[140:143], v[164:167], v[120:123]
	v_mfma_f32_16x16x32_bf16 v[108:111], v[132:135], v[172:175], v[108:111]
	v_mfma_f32_16x16x32_bf16 v[104:107], v[140:143], v[172:175], v[104:107]
	v_mfma_f32_16x16x32_bf16 v[92:95], v[132:135], v[180:183], v[92:95]
	v_mfma_f32_16x16x32_bf16 v[88:91], v[140:143], v[180:183], v[88:91]
	v_mfma_f32_16x16x32_bf16 v[76:79], v[132:135], v[188:191], v[76:79]
	v_mfma_f32_16x16x32_bf16 v[72:75], v[140:143], v[188:191], v[72:75]
	s_setprio 0
	s_setprio 1
	v_mfma_f32_16x16x32_bf16 v[116:119], v[144:147], v[160:163], 0
	v_mfma_f32_16x16x32_bf16 v[112:115], v[152:155], v[160:163], 0
	v_mfma_f32_16x16x32_bf16 v[100:103], v[144:147], v[168:171], 0
	v_mfma_f32_16x16x32_bf16 v[96:99], v[152:155], v[168:171], 0
	v_mfma_f32_16x16x32_bf16 v[84:87], v[144:147], v[176:179], 0
	v_mfma_f32_16x16x32_bf16 v[80:83], v[152:155], v[176:179], 0
	v_mfma_f32_16x16x32_bf16 v[68:71], v[144:147], v[184:187], 0
	v_mfma_f32_16x16x32_bf16 v[64:67], v[152:155], v[184:187], 0
	v_mfma_f32_16x16x32_bf16 v[116:119], v[148:151], v[164:167], v[116:119]
	v_mfma_f32_16x16x32_bf16 v[112:115], v[156:159], v[164:167], v[112:115]
	v_mfma_f32_16x16x32_bf16 v[100:103], v[148:151], v[172:175], v[100:103]
	v_mfma_f32_16x16x32_bf16 v[96:99], v[156:159], v[172:175], v[96:99]
	v_mfma_f32_16x16x32_bf16 v[84:87], v[148:151], v[180:183], v[84:87]
	v_mfma_f32_16x16x32_bf16 v[80:83], v[156:159], v[180:183], v[80:83]
	v_mfma_f32_16x16x32_bf16 v[68:71], v[148:151], v[188:191], v[68:71]
	v_mfma_f32_16x16x32_bf16 v[64:67], v[156:159], v[188:191], v[64:67]
	s_setprio 0
	s_barrier
	s_add_i32 s74, s74, s54
	v_lshl_add_u64 v[212:213], s[72:73], 0, v[192:193]
	s_mov_b32 m0, s74
	ds_read_b128 v[160:163], v247 offset:16384
	ds_read_b128 v[164:167], v247 offset:17408
	ds_read_b128 v[168:171], v247 offset:18432
	ds_read_b128 v[172:175], v247 offset:19456
	ds_read_b128 v[176:179], v247 offset:20480
	ds_read_b128 v[180:183], v247 offset:21504
	ds_read_b128 v[184:187], v247 offset:22528
	ds_read_b128 v[188:191], v247 offset:23552
	global_load_lds_dwordx4 v[212:213], off
	s_add_i32 m0, s74, 0x2000
	v_lshl_add_u64 v[214:215], s[72:73], 0, v[204:205]
	s_add_u32 s72, s72, s2
	s_addc_u32 s73, s73, 0
	s_add_i32 s74, s75, s54
	global_load_lds_dwordx4 v[214:215], off
	v_lshl_add_u64 v[216:217], s[72:73], 0, v[192:193]
	s_mov_b32 m0, s74
	v_lshl_add_u64 v[218:219], s[72:73], 0, v[204:205]
	global_load_lds_dwordx4 v[216:217], off
	s_add_i32 m0, s74, 0x2000
	v_lshl_add_u64 v[220:221], s[4:5], 0, v[200:201]
	global_load_lds_dwordx4 v[218:219], off
	s_mov_b32 m0, s55
	v_lshl_add_u64 v[222:223], s[4:5], 0, v[202:203]
	global_load_lds_dwordx4 v[220:221], off
	s_mov_b32 m0, s56
	s_nop 0
	global_load_lds_dwordx4 v[222:223], off
	s_waitcnt vmcnt(8)
	s_waitcnt lgkmcnt(0)
	s_barrier
; #define PG8_STAGE(bufoff, gbase, voff) do { _Pragma("unroll") for (int _i = 0; _i < 2; ++_i) \
;         __builtin_amdgcn_global_load_lds((const unsigned*)((const char*)(gbase) + (voff)[_i]), (LAS unsigned*)(lds + (bufoff) + ldsw + _i * 8192), 16, 0, 0); } while (0)
; #define PG8_LDA(dst, b, h) do { _Pragma("unroll") for (int m = 0; m < 4; ++m) _Pragma("unroll") for (int k = 0; k < 2; ++k) dst[m][k] = *(const LAS bf16x8*)(lds + PG8_SA(b, h) + aoff + m * 2048 + k * 1024); } while (0)
; #define PG8_LDB(dst, b, h) do { _Pragma("unroll") for (int n = 0; n < 2; ++n) _Pragma("unroll") for (int k = 0; k < 2; ++k) dst[n][k] = *(const LAS bf16x8*)(lds + PG8_SB(b, h) + boff + n * 2048 + k * 1024); } while (0)
; #define PG8_MMA(ai, bj, At, Bt) do { __builtin_amdgcn_s_setprio(1); _Pragma("unroll") for (int m = 0; m < 4; ++m) _Pragma("unroll") for (int n = 0; n < 2; ++n) _Pragma("unroll") for (int k = 0; k < 2; ++k) \
;         acc[ai][bj][m][n] = __builtin_amdgcn_mfma_f32_16x16x32_bf16(Bt[n][k], At[m][k], acc[ai][bj][m][n], 0, 0, 0); __builtin_amdgcn_s_setprio(0); } while (0)
; #define PG8_WAIT_V(n) asm volatile("s_waitcnt vmcnt(" #n ")" ::: "memory")
; #define PG8_WAIT_L(n) asm volatile("s_waitcnt lgkmcnt(" #n ")" ::: "memory")
; #define PG8_BAR __builtin_amdgcn_s_barrier()
; #define PG8_SCHED __builtin_amdgcn_sched_barrier(0)
; template <class Epi>
; __device__ __forceinline__ void gemm_phase(LAS unsigned char* lds, const Gemm g, const StaticOrder& S, const Epi& E) {
;     ...
;             PG8_LDA(At, 0, 1); PG8_STAGE(PG8_SB(0, 0), b2, voffB); PG8_STAGE(PG8_SB(0, 1), b2 + hstep, voffB); PG8_STAGE(PG8_SA(0, 0), a2, voffA);
;             PG8_WAIT_V(8); PG8_WAIT_L(0); PG8_BAR; PG8_MMA(1, 0, At, B0); PG8_MMA(1, 1, At, B1); PG8_BAR; PG8_SCHED;
;             PG8_LDB(B0, 1, 0); PG8_LDB(B1, 1, 1); PG8_SCHED; PG8_LDA(At, 1, 0); PG8_STAGE(PG8_SA(0, 1), a2 + hstep, voffA);
;             PG8_WAIT_V(8); PG8_WAIT_L(0); PG8_BAR; PG8_MMA(0, 0, At, B0); PG8_MMA(0, 1, At, B1); PG8_BAR; PG8_SCHED;
	s_setprio 1
	s_waitcnt lgkmcnt(0)
	v_mfma_f32_16x16x32_bf16 v[60:63], v[128:131], v[160:163], 0
	v_mfma_f32_16x16x32_bf16 v[56:59], v[136:139], v[160:163], 0
	v_mfma_f32_16x16x32_bf16 v[44:47], v[128:131], v[168:171], 0
	v_mfma_f32_16x16x32_bf16 v[40:43], v[136:139], v[168:171], 0
	v_mfma_f32_16x16x32_bf16 v[28:31], v[128:131], v[176:179], 0
	v_mfma_f32_16x16x32_bf16 v[24:27], v[136:139], v[176:179], 0
	v_mfma_f32_16x16x32_bf16 v[12:15], v[128:131], v[184:187], 0
	v_mfma_f32_16x16x32_bf16 v[8:11], v[136:139], v[184:187], 0
	v_mfma_f32_16x16x32_bf16 v[60:63], v[132:135], v[164:167], v[60:63]
	v_mfma_f32_16x16x32_bf16 v[56:59], v[140:143], v[164:167], v[56:59]
	v_mfma_f32_16x16x32_bf16 v[44:47], v[132:135], v[172:175], v[44:47]
	v_mfma_f32_16x16x32_bf16 v[40:43], v[140:143], v[172:175], v[40:43]
	v_mfma_f32_16x16x32_bf16 v[28:31], v[132:135], v[180:183], v[28:31]
	v_mfma_f32_16x16x32_bf16 v[24:27], v[140:143], v[180:183], v[24:27]
	v_mfma_f32_16x16x32_bf16 v[12:15], v[132:135], v[188:191], v[12:15]
	v_mfma_f32_16x16x32_bf16 v[8:11], v[140:143], v[188:191], v[8:11]
	s_setprio 0
	s_setprio 1
	v_mfma_f32_16x16x32_bf16 v[52:55], v[144:147], v[160:163], 0
	v_mfma_f32_16x16x32_bf16 v[48:51], v[152:155], v[160:163], 0
	v_mfma_f32_16x16x32_bf16 v[36:39], v[144:147], v[168:171], 0
	v_mfma_f32_16x16x32_bf16 v[32:35], v[152:155], v[168:171], 0
	v_mfma_f32_16x16x32_bf16 v[20:23], v[144:147], v[176:179], 0
	v_mfma_f32_16x16x32_bf16 v[16:19], v[152:155], v[176:179], 0
	v_mfma_f32_16x16x32_bf16 v[4:7], v[144:147], v[184:187], 0
	v_mfma_f32_16x16x32_bf16 v[0:3], v[152:155], v[184:187], 0
	v_mfma_f32_16x16x32_bf16 v[52:55], v[148:151], v[164:167], v[52:55]
	v_mfma_f32_16x16x32_bf16 v[48:51], v[156:159], v[164:167], v[48:51]
	v_mfma_f32_16x16x32_bf16 v[36:39], v[148:151], v[172:175], v[36:39]
	v_mfma_f32_16x16x32_bf16 v[32:35], v[156:159], v[172:175], v[32:35]
	v_mfma_f32_16x16x32_bf16 v[20:23], v[148:151], v[180:183], v[20:23]
	v_mfma_f32_16x16x32_bf16 v[16:19], v[156:159], v[180:183], v[16:19]
	v_mfma_f32_16x16x32_bf16 v[4:7], v[148:151], v[188:191], v[4:7]
	v_mfma_f32_16x16x32_bf16 v[0:3], v[156:159], v[188:191], v[0:3]
	s_setprio 0
	s_barrier
	s_add_i32 s72, 0, 0x18000
	s_add_i32 s73, 0, 0x1c000
	v_add_u32_e32 v140, s72, v245
	v_add_u32_e32 v156, s73, v245
	ds_read_b128 v[128:131], v140
	ds_read_b128 v[132:135], v140 offset:1024
	ds_read_b128 v[136:139], v140 offset:2048
	ds_read_b128 v[140:143], v140 offset:3072
	ds_read_b128 v[144:147], v156
	ds_read_b128 v[148:151], v156 offset:1024
	ds_read_b128 v[152:155], v156 offset:2048
	ds_read_b128 v[156:159], v156 offset:3072
	s_add_u32 s4, s4, s2
	s_addc_u32 s5, s5, 0
	s_mov_b32 m0, s57
	v_lshl_add_u64 v[224:225], s[4:5], 0, v[200:201]
	ds_read_b128 v[160:163], v247 offset:32768
	ds_read_b128 v[164:167], v247 offset:33792
	ds_read_b128 v[168:171], v247 offset:34816
	ds_read_b128 v[172:175], v247 offset:35840
	ds_read_b128 v[176:179], v247 offset:36864
	ds_read_b128 v[180:183], v247 offset:37888
	ds_read_b128 v[184:187], v247 offset:38912
	ds_read_b128 v[188:191], v247 offset:39936
	global_load_lds_dwordx4 v[224:225], off
	v_lshl_add_u64 v[224:225], s[4:5], 0, v[202:203]
	s_mov_b32 m0, s58
	s_nop 0
	global_load_lds_dwordx4 v[224:225], off
	s_waitcnt vmcnt(8)
	s_waitcnt lgkmcnt(0)
	s_barrier
	s_setprio 1
	s_waitcnt lgkmcnt(0)
	v_mfma_f32_16x16x32_bf16 v[124:127], v[128:131], v[160:163], v[124:127]
	v_mfma_f32_16x16x32_bf16 v[120:123], v[136:139], v[160:163], v[120:123]
	v_mfma_f32_16x16x32_bf16 v[108:111], v[128:131], v[168:171], v[108:111]
	v_mfma_f32_16x16x32_bf16 v[104:107], v[136:139], v[168:171], v[104:107]
	v_mfma_f32_16x16x32_bf16 v[92:95], v[128:131], v[176:179], v[92:95]
	v_mfma_f32_16x16x32_bf16 v[88:91], v[136:139], v[176:179], v[88:91]
	v_mfma_f32_16x16x32_bf16 v[76:79], v[128:131], v[184:187], v[76:79]
	v_mfma_f32_16x16x32_bf16 v[72:75], v[136:139], v[184:187], v[72:75]
	v_mfma_f32_16x16x32_bf16 v[124:127], v[132:135], v[164:167], v[124:127]
	v_mfma_f32_16x16x32_bf16 v[120:123], v[140:143], v[164:167], v[120:123]
	v_mfma_f32_16x16x32_bf16 v[108:111], v[132:135], v[172:175], v[108:111]
	v_mfma_f32_16x16x32_bf16 v[104:107], v[140:143], v[172:175], v[104:107]
	v_mfma_f32_16x16x32_bf16 v[92:95], v[132:135], v[180:183], v[92:95]
	v_mfma_f32_16x16x32_bf16 v[88:91], v[140:143], v[180:183], v[88:91]
	v_mfma_f32_16x16x32_bf16 v[76:79], v[132:135], v[188:191], v[76:79]
	v_mfma_f32_16x16x32_bf16 v[72:75], v[140:143], v[188:191], v[72:75]
	s_setprio 0
	s_setprio 1
	v_mfma_f32_16x16x32_bf16 v[116:119], v[144:147], v[160:163], v[116:119]
	v_mfma_f32_16x16x32_bf16 v[112:115], v[152:155], v[160:163], v[112:115]
	v_mfma_f32_16x16x32_bf16 v[100:103], v[144:147], v[168:171], v[100:103]
	v_mfma_f32_16x16x32_bf16 v[96:99], v[152:155], v[168:171], v[96:99]
	v_mfma_f32_16x16x32_bf16 v[84:87], v[144:147], v[176:179], v[84:87]
	v_mfma_f32_16x16x32_bf16 v[80:83], v[152:155], v[176:179], v[80:83]
	v_mfma_f32_16x16x32_bf16 v[68:71], v[144:147], v[184:187], v[68:71]
	v_mfma_f32_16x16x32_bf16 v[64:67], v[152:155], v[184:187], v[64:67]
	v_mfma_f32_16x16x32_bf16 v[116:119], v[148:151], v[164:167], v[116:119]
	v_mfma_f32_16x16x32_bf16 v[112:115], v[156:159], v[164:167], v[112:115]
	v_mfma_f32_16x16x32_bf16 v[100:103], v[148:151], v[172:175], v[100:103]
	v_mfma_f32_16x16x32_bf16 v[96:99], v[156:159], v[172:175], v[96:99]
	v_mfma_f32_16x16x32_bf16 v[84:87], v[148:151], v[180:183], v[84:87]
	v_mfma_f32_16x16x32_bf16 v[80:83], v[156:159], v[180:183], v[80:83]
	v_mfma_f32_16x16x32_bf16 v[68:71], v[148:151], v[188:191], v[68:71]
	v_mfma_f32_16x16x32_bf16 v[64:67], v[156:159], v[188:191], v[64:67]
	s_setprio 0
	s_barrier
; #define PG8_STAGE(bufoff, gbase, voff) do { _Pragma("unroll") for (int _i = 0; _i < 2; ++_i) \
;         __builtin_amdgcn_global_load_lds((const unsigned*)((const char*)(gbase) + (voff)[_i]), (LAS unsigned*)(lds + (bufoff) + ldsw + _i * 8192), 16, 0, 0); } while (0)
; #define PG8_LDA(dst, b, h) do { _Pragma("unroll") for (int m = 0; m < 4; ++m) _Pragma("unroll") for (int k = 0; k < 2; ++k) dst[m][k] = *(const LAS bf16x8*)(lds + PG8_SA(b, h) + aoff + m * 2048 + k * 1024); } while (0)
; #define PG8_MMA(ai, bj, At, Bt) do { __builtin_amdgcn_s_setprio(1); _Pragma("unroll") for (int m = 0; m < 4; ++m) _Pragma("unroll") for (int n = 0; n < 2; ++n) _Pragma("unroll") for (int k = 0; k < 2; ++k) \
;         acc[ai][bj][m][n] = __builtin_amdgcn_mfma_f32_16x16x32_bf16(Bt[n][k], At[m][k], acc[ai][bj][m][n], 0, 0, 0); __builtin_amdgcn_s_setprio(0); } while (0)
; #define PG8_WAIT_V(n) asm volatile("s_waitcnt vmcnt(" #n ")" ::: "memory")
; #define PG8_WAIT_L(n) asm volatile("s_waitcnt lgkmcnt(" #n ")" ::: "memory")
; #define PG8_BAR __builtin_amdgcn_s_barrier()
; #define PG8_SCHED __builtin_amdgcn_sched_barrier(0)
; template <class Epi>
; __device__ __forceinline__ void gemm_phase(LAS unsigned char* lds, const Gemm g, const StaticOrder& S, const Epi& E) {
;     ...
;             PG8_LDA(At, 1, 1); PG8_STAGE(PG8_SB(1, 0), b3, voffB); PG8_STAGE(PG8_SB(1, 1), b3 + hstep, voffB); PG8_STAGE(PG8_SA(1, 0), a3, voffA);
;             PG8_WAIT_V(8); PG8_WAIT_L(0); PG8_BAR; PG8_MMA(1, 0, At, B0); PG8_MMA(1, 1, At, B1); PG8_BAR; PG8_SCHED;
;         }
	s_add_i32 s4, s72, s54
	v_lshl_add_u64 v[212:213], v[212:213], 0, s[12:13]
	s_mov_b32 m0, s4
	ds_read_b128 v[160:163], v247 offset:49152
	ds_read_b128 v[164:167], v247 offset:50176
	ds_read_b128 v[168:171], v247 offset:51200
	ds_read_b128 v[172:175], v247 offset:52224
	ds_read_b128 v[176:179], v247 offset:53248
	ds_read_b128 v[180:183], v247 offset:54272
	ds_read_b128 v[184:187], v247 offset:55296
	ds_read_b128 v[188:191], v247 offset:56320
	global_load_lds_dwordx4 v[212:213], off
	v_lshl_add_u64 v[212:213], v[214:215], 0, s[12:13]
	s_add_i32 m0, s4, 0x2000
	s_add_i32 s4, s73, s54
	global_load_lds_dwordx4 v[212:213], off
	v_lshl_add_u64 v[212:213], v[216:217], 0, s[12:13]
	s_mov_b32 m0, s4
	s_nop 0
	global_load_lds_dwordx4 v[212:213], off
	v_lshl_add_u64 v[212:213], v[218:219], 0, s[12:13]
	s_add_i32 m0, s4, 0x2000
	s_nop 0
	global_load_lds_dwordx4 v[212:213], off
	v_lshl_add_u64 v[212:213], v[220:221], 0, s[12:13]
	s_mov_b32 m0, s59
	s_nop 0
	global_load_lds_dwordx4 v[212:213], off
	v_lshl_add_u64 v[212:213], v[222:223], 0, s[12:13]
	s_mov_b32 m0, s60
	s_nop 0
	global_load_lds_dwordx4 v[212:213], off
	s_waitcnt vmcnt(8)
	s_waitcnt lgkmcnt(0)
	s_barrier
	s_setprio 1
	s_waitcnt lgkmcnt(0)
	v_mfma_f32_16x16x32_bf16 v[60:63], v[128:131], v[160:163], v[60:63]
	v_mfma_f32_16x16x32_bf16 v[56:59], v[136:139], v[160:163], v[56:59]
	v_mfma_f32_16x16x32_bf16 v[44:47], v[128:131], v[168:171], v[44:47]
	v_mfma_f32_16x16x32_bf16 v[40:43], v[136:139], v[168:171], v[40:43]
	v_mfma_f32_16x16x32_bf16 v[28:31], v[128:131], v[176:179], v[28:31]
	v_mfma_f32_16x16x32_bf16 v[24:27], v[136:139], v[176:179], v[24:27]
	v_mfma_f32_16x16x32_bf16 v[12:15], v[128:131], v[184:187], v[12:15]
	v_mfma_f32_16x16x32_bf16 v[8:11], v[136:139], v[184:187], v[8:11]
	v_mfma_f32_16x16x32_bf16 v[60:63], v[132:135], v[164:167], v[60:63]
	v_mfma_f32_16x16x32_bf16 v[56:59], v[140:143], v[164:167], v[56:59]
	v_mfma_f32_16x16x32_bf16 v[44:47], v[132:135], v[172:175], v[44:47]
	v_mfma_f32_16x16x32_bf16 v[40:43], v[140:143], v[172:175], v[40:43]
	v_mfma_f32_16x16x32_bf16 v[28:31], v[132:135], v[180:183], v[28:31]
	v_mfma_f32_16x16x32_bf16 v[24:27], v[140:143], v[180:183], v[24:27]
	v_mfma_f32_16x16x32_bf16 v[12:15], v[132:135], v[188:191], v[12:15]
	v_mfma_f32_16x16x32_bf16 v[8:11], v[140:143], v[188:191], v[8:11]
	s_setprio 0
	s_setprio 1
	v_mfma_f32_16x16x32_bf16 v[52:55], v[144:147], v[160:163], v[52:55]
	v_mfma_f32_16x16x32_bf16 v[48:51], v[152:155], v[160:163], v[48:51]
	v_mfma_f32_16x16x32_bf16 v[36:39], v[144:147], v[168:171], v[36:39]
	v_mfma_f32_16x16x32_bf16 v[32:35], v[152:155], v[168:171], v[32:35]
	v_mfma_f32_16x16x32_bf16 v[20:23], v[144:147], v[176:179], v[20:23]
	v_mfma_f32_16x16x32_bf16 v[16:19], v[152:155], v[176:179], v[16:19]
	v_mfma_f32_16x16x32_bf16 v[4:7], v[144:147], v[184:187], v[4:7]
	v_mfma_f32_16x16x32_bf16 v[0:3], v[152:155], v[184:187], v[0:3]
	v_mfma_f32_16x16x32_bf16 v[52:55], v[148:151], v[164:167], v[52:55]
	v_mfma_f32_16x16x32_bf16 v[48:51], v[156:159], v[164:167], v[48:51]
	v_mfma_f32_16x16x32_bf16 v[36:39], v[148:151], v[172:175], v[36:39]
	v_mfma_f32_16x16x32_bf16 v[32:35], v[156:159], v[172:175], v[32:35]
	v_mfma_f32_16x16x32_bf16 v[20:23], v[148:151], v[180:183], v[20:23]
	v_mfma_f32_16x16x32_bf16 v[16:19], v[156:159], v[180:183], v[16:19]
	v_mfma_f32_16x16x32_bf16 v[4:7], v[148:151], v[188:191], v[4:7]
	v_mfma_f32_16x16x32_bf16 v[0:3], v[156:159], v[188:191], v[0:3]
	s_setprio 0
	s_barrier
	s_add_u32 s0, s0, 0x100
	s_addc_u32 s1, s1, 0
	s_add_u32 s6, s6, 0x100
	s_addc_u32 s7, s7, 0
	s_cmp_ge_u32 s71, s61
	s_mov_b32 s4, s71
	s_cbranch_scc1 .Lk_done

; #define PG8_BAR __builtin_amdgcn_s_barrier()
; template <class Epi>
; __device__ __forceinline__ void gemm_phase(LAS unsigned char* lds, const Gemm g, const StaticOrder& S, const Epi& E) {
;     ...
;         }
;         if (wr == 0) PG8_BAR;
;         E(acc, cur, wr, wc, fr, fq);
;         if (!has_next) break;
.Lk_done:
	s_and_b64 vcc, exec, s[44:45]
	s_cbranch_vccz .LBB0_225
	s_barrier
